# x-rows prep loop: all 8 chunk loads of a row issued up front with counted vmcnt(7) waits; plus hand-written prep conversion and LDS-staged S5 carry scan
# speedup vs baseline: 1.0047x; 1.0009x over previous
; __device__ __forceinline__ unsigned cvt_pk_bf16(float lo, float hi) { unsigned r; asm volatile("v_cvt_pk_bf16_f32 %0, %1, %2" : "=v"(r) : "v"(lo), "v"(hi)); return r; }
; __device__ __forceinline__ float bf_lo(unsigned w) { return __uint_as_float(w << 16); }
; __device__ __forceinline__ float bf_hi(unsigned w) { return __uint_as_float(w & 0xffff0000u); }
; __global__ void __launch_bounds__(NTHR) hybrid_encoder_fwd(Params P) {
;     ...
;             const float* x = P.in[0];
;             for (int row = bid * 8 + wid; row < SEQ; row += G * 8) {
;                 float ss = 0.f;
; #pragma unroll
;                 for (int i = 0; i < 8; ++i) { const int c = lane * 4 + 256 * i; const f32x4 v = *(const f32x4*)(x + (size_t)row * DM + c);
;                     u32x2 w; w.x = cvt_pk_bf16(v[0], v[1]); w.y = cvt_pk_bf16(v[2], v[3]);
;                     const float r0 = bf_lo(w.x), r1 = bf_hi(w.x), r2 = bf_lo(w.y), r3 = bf_hi(w.y); ss += (r0 * r0 + r1 * r1) + (r2 * r2 + r3 * r3);
;                     *(u32x2*)(XG + (size_t)row * DM + c) = w; }
;                 ss += __shfl_xor(ss, 32);
;                 if (lane < 32) SSQ[(size_t)row * 32 + lane] = ss;
;             }
.LBB0_8:
	v_lshl_add_u64 v[16:17], s[96:97], 0, v[4:5]
	v_add_co_u32_e64 v16, s[0:1], s3, v16
	s_waitcnt lgkmcnt(0)
	global_load_dwordx4 v[40:43], v[6:7], off offset:-4096
	global_load_dwordx4 v[44:47], v[6:7], off offset:-3072
	global_load_dwordx4 v[48:51], v[6:7], off offset:-2048
	global_load_dwordx4 v[52:55], v[6:7], off offset:-1024
	global_load_dwordx4 v[56:59], v[6:7], off offset:0
	global_load_dwordx4 v[60:63], v[6:7], off offset:1024
	global_load_dwordx4 v[64:67], v[6:7], off offset:2048
	global_load_dwordx4 v[68:71], v[6:7], off offset:3072
	v_addc_co_u32_e64 v17, s[0:1], 0, v17, s[0:1]
	s_waitcnt vmcnt(7)
	v_cvt_pk_bf16_f32 v18, v40, v41
	v_cvt_pk_bf16_f32 v19, v42, v43
	global_store_dwordx2 v[16:17], v[18:19], off
	v_lshlrev_b32_e32 v11, 16, v18
	v_and_b32_e32 v18, 0xffff0000, v18
	v_lshlrev_b32_e32 v33, 16, v19
	v_and_b32_e32 v19, 0xffff0000, v19
	v_mul_f32_e32 v18, v18, v18
	v_mul_f32_e32 v19, v19, v19
	s_waitcnt vmcnt(7)
	v_cvt_pk_bf16_f32 v20, v44, v45
	v_cvt_pk_bf16_f32 v21, v46, v47
	v_fmac_f32_e32 v18, v11, v11
	v_fmac_f32_e32 v19, v33, v33
	global_store_dwordx2 v[16:17], v[20:21], off offset:512
	v_add_f32_e32 v11, v18, v19
	v_lshlrev_b32_e32 v18, 16, v20
	v_and_b32_e32 v19, 0xffff0000, v20
	v_lshlrev_b32_e32 v20, 16, v21
	v_and_b32_e32 v21, 0xffff0000, v21
	v_mul_f32_e32 v19, v19, v19
	v_mul_f32_e32 v21, v21, v21
	v_fmac_f32_e32 v19, v18, v18
	v_fmac_f32_e32 v21, v20, v20
	s_waitcnt vmcnt(7)
	v_cvt_pk_bf16_f32 v22, v48, v49
	v_cvt_pk_bf16_f32 v23, v50, v51
	v_add_f32_e32 v18, v19, v21
	v_and_b32_e32 v19, 0xffff0000, v22
	v_and_b32_e32 v21, 0xffff0000, v23
	v_add_f32_e32 v11, v11, v18
	v_lshlrev_b32_e32 v18, 16, v22
	v_lshlrev_b32_e32 v20, 16, v23
	v_mul_f32_e32 v19, v19, v19
	v_mul_f32_e32 v21, v21, v21
	global_store_dwordx2 v[16:17], v[22:23], off offset:1024
	v_fmac_f32_e32 v19, v18, v18
	v_fmac_f32_e32 v21, v20, v20
	s_waitcnt vmcnt(7)
	v_cvt_pk_bf16_f32 v24, v52, v53
	v_cvt_pk_bf16_f32 v25, v54, v55
	v_add_f32_e32 v18, v19, v21
	v_and_b32_e32 v19, 0xffff0000, v24
	v_and_b32_e32 v21, 0xffff0000, v25
	v_add_f32_e32 v11, v11, v18
	v_lshlrev_b32_e32 v18, 16, v24
	v_lshlrev_b32_e32 v20, 16, v25
	v_mul_f32_e32 v19, v19, v19
	v_mul_f32_e32 v21, v21, v21
	global_store_dwordx2 v[16:17], v[24:25], off offset:1536
	v_fmac_f32_e32 v19, v18, v18
	v_fmac_f32_e32 v21, v20, v20
	s_waitcnt vmcnt(7)
	v_cvt_pk_bf16_f32 v26, v56, v57
	v_cvt_pk_bf16_f32 v27, v58, v59
	v_add_f32_e32 v18, v19, v21
	v_and_b32_e32 v19, 0xffff0000, v26
	v_and_b32_e32 v21, 0xffff0000, v27
	v_add_f32_e32 v11, v11, v18
	v_lshlrev_b32_e32 v18, 16, v26
	v_lshlrev_b32_e32 v20, 16, v27
	v_mul_f32_e32 v19, v19, v19
	v_mul_f32_e32 v21, v21, v21
	global_store_dwordx2 v[16:17], v[26:27], off offset:2048
	v_fmac_f32_e32 v19, v18, v18
	v_fmac_f32_e32 v21, v20, v20
	s_waitcnt vmcnt(7)
	v_cvt_pk_bf16_f32 v28, v60, v61
	v_cvt_pk_bf16_f32 v29, v62, v63
	v_add_f32_e32 v18, v19, v21
	v_and_b32_e32 v19, 0xffff0000, v28
	v_and_b32_e32 v21, 0xffff0000, v29
	v_add_f32_e32 v11, v11, v18
	v_lshlrev_b32_e32 v18, 16, v28
	v_lshlrev_b32_e32 v20, 16, v29
	v_mul_f32_e32 v19, v19, v19
	v_mul_f32_e32 v21, v21, v21
	global_store_dwordx2 v[16:17], v[28:29], off offset:2560
	v_fmac_f32_e32 v19, v18, v18
	v_fmac_f32_e32 v21, v20, v20
	s_waitcnt vmcnt(7)
	v_cvt_pk_bf16_f32 v30, v64, v65
	v_cvt_pk_bf16_f32 v31, v66, v67
	v_add_f32_e32 v18, v19, v21
	v_and_b32_e32 v19, 0xffff0000, v30
	v_and_b32_e32 v21, 0xffff0000, v31
	v_add_f32_e32 v11, v11, v18
	v_lshlrev_b32_e32 v18, 16, v30
	v_lshlrev_b32_e32 v20, 16, v31
	v_mul_f32_e32 v19, v19, v19
	v_mul_f32_e32 v21, v21, v21
	global_store_dwordx2 v[16:17], v[30:31], off offset:3072
	v_fmac_f32_e32 v19, v18, v18
	v_fmac_f32_e32 v21, v20, v20
	v_add_f32_e32 v18, v19, v21
	v_add_f32_e32 v11, v11, v18
	s_waitcnt vmcnt(7)
	v_cvt_pk_bf16_f32 v18, v68, v69
	v_cvt_pk_bf16_f32 v19, v70, v71
	v_cmp_lt_i32_e64 s[0:1], v9, v10
	v_and_b32_e32 v13, 0xffff0000, v18
	v_and_b32_e32 v15, 0xffff0000, v19
	v_lshlrev_b32_e32 v12, 16, v18
	v_lshlrev_b32_e32 v14, 16, v19
	v_mul_f32_e32 v13, v13, v13
	v_mul_f32_e32 v15, v15, v15
	v_fmac_f32_e32 v13, v12, v12
	v_fmac_f32_e32 v15, v14, v14
	v_cndmask_b32_e64 v32, v8, v9, s[0:1]
	v_add_f32_e32 v12, v13, v15
	v_add_f32_e32 v11, v11, v12
	v_lshlrev_b32_e32 v12, 2, v32
	ds_bpermute_b32 v12, v12, v11
	global_store_dwordx2 v[16:17], v[18:19], off offset:3584
	s_and_saveexec_b64 s[0:1], vcc
	s_cbranch_execz .LBB0_7
	v_lshl_add_u64 v[14:15], s[96:97], 0, v[2:3]
	s_waitcnt lgkmcnt(0)
	v_add_f32_e32 v11, v11, v12
	global_store_dword v[14:15], v11, off
	s_branch .LBB0_7
